# plus phase-1 non-V epilogue: dwordx2 row-store pairs merged into dwordx4 via v_permlane16_swap
# speedup vs baseline: 1.0170x; 1.0033x over previous
; DI unsigned pack2(float lo, float hi) { f2_t v = {lo, hi}; h2_t b = __builtin_convertvector(v, h2_t); return __builtin_bit_cast(unsigned, b); }
; DI float sigmoidf_(float x) { return 1.0f / (1.0f + __expf(-x)); }
; DI void phase_proj(const Params& P, int l, char* smem) {
;     ...
; #pragma unroll
;       for (int mt = 0; mt < 4; ++mt) {
;         const int row = row0 + mt * 16 + lr;
; #pragma unroll
;         for (int nt = 0; nt < 4; ++nt) {
;           f32x4 v = acc[mt][nt] * sc;
;           if (sig) { v[0] = sigmoidf_(v[0]); v[1] = sigmoidf_(v[1]); v[2] = sigmoidf_(v[2]); v[3] = sigmoidf_(v[3]); }
;           *(uint2*)(Pb + (size_t)row * PW + col0 + nt * 16 + 4 * g) = make_uint2(pack2(v[0], v[1]), pack2(v[2], v[3]));
;         }
;       }
.LBB0_660:
	s_or_b64 exec, exec, s[4:5]
	v_ashrrev_i32_e32 v95, 31, v94
	v_mov_b32_e32 v73, v72
	v_lshl_add_u64 v[28:29], v[94:95], 1, v[90:91]
	v_cvt_pk_f16_f32 v34, v34, v35
	v_cvt_pk_f16_f32 v35, v32, v33
	v_mov_b32_e32 v32, v72
	v_mov_b32_e32 v33, v72
	v_mad_i64_i32 v[30:31], s[4:5], v70, s0, v[28:29]
	v_pk_mul_f32 v[26:27], v[32:33], v[26:27]
	v_pk_mul_f32 v[24:25], v[72:73], v[24:25]
	v_mov_b32_e32 v220, v34
	v_mov_b32_e32 v221, v35
	s_and_saveexec_b64 s[4:5], s[20:21]
	s_cbranch_execz .LBB0_662
	v_mul_f32_e32 v26, 0xbfb8aa3b, v26
	v_mul_f32_e32 v27, 0xbfb8aa3b, v27
	v_exp_f32_e32 v26, v26
	v_exp_f32_e32 v27, v27
	v_mul_f32_e32 v24, 0xbfb8aa3b, v24
	v_mul_f32_e32 v25, 0xbfb8aa3b, v25
	v_exp_f32_e32 v24, v24
	v_pk_add_f32 v[26:27], v[26:27], 1.0 op_sel_hi:[1,0]
	v_exp_f32_e32 v25, v25
	v_div_scale_f32 v34, s[22:23], v27, v27, 1.0
	v_rcp_f32_e32 v35, v34
	v_pk_add_f32 v[24:25], v[24:25], 1.0 op_sel_hi:[1,0]
	v_fma_f32 v36, -v34, v35, 1.0
	v_fmac_f32_e32 v35, v36, v35
	v_div_scale_f32 v36, vcc, 1.0, v27, 1.0
	v_mul_f32_e32 v37, v36, v35
	v_fma_f32 v38, -v34, v37, v36
	v_fmac_f32_e32 v37, v38, v35
	v_fma_f32 v34, -v34, v37, v36
	v_div_fmas_f32 v34, v34, v35, v37
	v_div_fixup_f32 v27, v34, v27, 1.0
	v_div_scale_f32 v34, s[22:23], v26, v26, 1.0
	v_rcp_f32_e32 v35, v34
	s_nop 0
	v_fma_f32 v36, -v34, v35, 1.0
	v_fmac_f32_e32 v35, v36, v35
	v_div_scale_f32 v36, vcc, 1.0, v26, 1.0
	v_mul_f32_e32 v37, v36, v35
	v_fma_f32 v38, -v34, v37, v36
	v_fmac_f32_e32 v37, v38, v35
	v_fma_f32 v34, -v34, v37, v36
	v_div_fmas_f32 v34, v34, v35, v37
	v_div_fixup_f32 v26, v34, v26, 1.0
	v_div_scale_f32 v34, s[22:23], v25, v25, 1.0
	v_rcp_f32_e32 v35, v34
	s_nop 0
	v_fma_f32 v36, -v34, v35, 1.0
	v_fmac_f32_e32 v35, v36, v35
	v_div_scale_f32 v36, vcc, 1.0, v25, 1.0
	v_mul_f32_e32 v37, v36, v35
	v_fma_f32 v38, -v34, v37, v36
	v_fmac_f32_e32 v37, v38, v35
	v_fma_f32 v34, -v34, v37, v36
	v_div_fmas_f32 v34, v34, v35, v37
	v_div_fixup_f32 v25, v34, v25, 1.0
	v_div_scale_f32 v34, s[22:23], v24, v24, 1.0
	v_rcp_f32_e32 v35, v34
	s_nop 0
	v_fma_f32 v36, -v34, v35, 1.0
	v_fmac_f32_e32 v35, v36, v35
	v_div_scale_f32 v36, vcc, 1.0, v24, 1.0
	v_mul_f32_e32 v37, v36, v35
	v_fma_f32 v38, -v34, v37, v36
	v_fmac_f32_e32 v37, v38, v35
	v_fma_f32 v34, -v34, v37, v36
	v_div_fmas_f32 v34, v34, v35, v37
	v_div_fixup_f32 v24, v34, v24, 1.0
.LBB0_662:
	s_or_b64 exec, exec, s[4:5]
	v_cvt_pk_f16_f32 v24, v24, v25
	v_cvt_pk_f16_f32 v25, v26, v27
	v_mov_b32_e32 v222, v24
	v_mov_b32_e32 v223, v25
	v_and_b32_e32 v236, 16, v148
	v_lshrrev_b32_e32 v237, 1, v236
	v_add_u32_e32 v236, v236, v237
	v_mov_b32_e32 v237, 0
	v_lshl_add_u64 v[236:237], v[236:237], 0, v[30:31]
	v_permlane16_swap_b32_e32 v220, v222
	v_permlane16_swap_b32_e32 v221, v223
	global_store_dwordx4 v[236:237], v[220:223], off
	v_pk_mul_f32 v[24:25], v[32:33], v[120:121]
	v_pk_mul_f32 v[26:27], v[72:73], v[118:119]
	s_and_saveexec_b64 s[4:5], s[20:21]
	s_cbranch_execz .LBB0_664
	v_mul_f32_e32 v24, 0xbfb8aa3b, v24
	v_mul_f32_e32 v25, 0xbfb8aa3b, v25
	v_exp_f32_e32 v24, v24
	v_exp_f32_e32 v25, v25
	v_mul_f32_e32 v26, 0xbfb8aa3b, v26
	v_mul_f32_e32 v27, 0xbfb8aa3b, v27
	v_exp_f32_e32 v26, v26
	v_pk_add_f32 v[24:25], v[24:25], 1.0 op_sel_hi:[1,0]
	v_exp_f32_e32 v27, v27
	v_div_scale_f32 v32, s[22:23], v25, v25, 1.0
	v_rcp_f32_e32 v33, v32
	v_pk_add_f32 v[26:27], v[26:27], 1.0 op_sel_hi:[1,0]
	v_fma_f32 v34, -v32, v33, 1.0
	v_fmac_f32_e32 v33, v34, v33
	v_div_scale_f32 v34, vcc, 1.0, v25, 1.0
	v_mul_f32_e32 v35, v34, v33
	v_fma_f32 v36, -v32, v35, v34
	v_fmac_f32_e32 v35, v36, v33
	v_fma_f32 v32, -v32, v35, v34
	v_div_fmas_f32 v32, v32, v33, v35
	v_div_fixup_f32 v25, v32, v25, 1.0
	v_div_scale_f32 v32, s[22:23], v24, v24, 1.0
	v_rcp_f32_e32 v33, v32
	s_nop 0
	v_fma_f32 v34, -v32, v33, 1.0
	v_fmac_f32_e32 v33, v34, v33
	v_div_scale_f32 v34, vcc, 1.0, v24, 1.0
	v_mul_f32_e32 v35, v34, v33
	v_fma_f32 v36, -v32, v35, v34
	v_fmac_f32_e32 v35, v36, v33
	v_fma_f32 v32, -v32, v35, v34
	v_div_fmas_f32 v32, v32, v33, v35
	v_div_fixup_f32 v24, v32, v24, 1.0
	v_div_scale_f32 v32, s[22:23], v27, v27, 1.0
	v_rcp_f32_e32 v33, v32
	s_nop 0
	v_fma_f32 v34, -v32, v33, 1.0
	v_fmac_f32_e32 v33, v34, v33
	v_div_scale_f32 v34, vcc, 1.0, v27, 1.0
	v_mul_f32_e32 v35, v34, v33
	v_fma_f32 v36, -v32, v35, v34
	v_fmac_f32_e32 v35, v36, v33
	v_fma_f32 v32, -v32, v35, v34
	v_div_fmas_f32 v32, v32, v33, v35
	v_div_fixup_f32 v27, v32, v27, 1.0
	v_div_scale_f32 v32, s[22:23], v26, v26, 1.0
	v_rcp_f32_e32 v33, v32
	s_nop 0
	v_fma_f32 v34, -v32, v33, 1.0
	v_fmac_f32_e32 v33, v34, v33
	v_div_scale_f32 v34, vcc, 1.0, v26, 1.0
	v_mul_f32_e32 v35, v34, v33
	v_fma_f32 v36, -v32, v35, v34
	v_fmac_f32_e32 v35, v36, v33
	v_fma_f32 v32, -v32, v35, v34
	v_div_fmas_f32 v32, v32, v33, v35
	v_div_fixup_f32 v26, v32, v26, 1.0
; DI unsigned pack2(float lo, float hi) { f2_t v = {lo, hi}; h2_t b = __builtin_convertvector(v, h2_t); return __builtin_bit_cast(unsigned, b); }
; DI float sigmoidf_(float x) { return 1.0f / (1.0f + __expf(-x)); }
; DI void phase_proj(const Params& P, int l, char* smem) {
;     ...
; #pragma unroll
;       for (int mt = 0; mt < 4; ++mt) {
;         const int row = row0 + mt * 16 + lr;
; #pragma unroll
;         for (int nt = 0; nt < 4; ++nt) {
;           f32x4 v = acc[mt][nt] * sc;
;           if (sig) { v[0] = sigmoidf_(v[0]); v[1] = sigmoidf_(v[1]); v[2] = sigmoidf_(v[2]); v[3] = sigmoidf_(v[3]); }
;           *(uint2*)(Pb + (size_t)row * PW + col0 + nt * 16 + 4 * g) = make_uint2(pack2(v[0], v[1]), pack2(v[2], v[3]));
;         }
;       }
.LBB0_664:
	s_or_b64 exec, exec, s[4:5]
	v_cvt_pk_f16_f32 v26, v26, v27
	v_cvt_pk_f16_f32 v27, v24, v25
	v_mov_b32_e32 v24, v72
	v_mov_b32_e32 v25, v72
	v_mov_b32_e32 v224, v26
	v_mov_b32_e32 v225, v27
	v_pk_mul_f32 v[26:27], v[24:25], v[116:117]
	v_pk_mul_f32 v[32:33], v[72:73], v[114:115]
	s_and_saveexec_b64 s[4:5], s[20:21]
	s_cbranch_execz .LBB0_666
	v_mul_f32_e32 v26, 0xbfb8aa3b, v26
	v_mul_f32_e32 v27, 0xbfb8aa3b, v27
	v_exp_f32_e32 v26, v26
	v_exp_f32_e32 v27, v27
	v_mul_f32_e32 v32, 0xbfb8aa3b, v32
	v_mul_f32_e32 v33, 0xbfb8aa3b, v33
	v_exp_f32_e32 v32, v32
	v_pk_add_f32 v[26:27], v[26:27], 1.0 op_sel_hi:[1,0]
	v_exp_f32_e32 v33, v33
	v_div_scale_f32 v34, s[22:23], v27, v27, 1.0
	v_rcp_f32_e32 v35, v34
	v_pk_add_f32 v[32:33], v[32:33], 1.0 op_sel_hi:[1,0]
	v_fma_f32 v36, -v34, v35, 1.0
	v_fmac_f32_e32 v35, v36, v35
	v_div_scale_f32 v36, vcc, 1.0, v27, 1.0
	v_mul_f32_e32 v37, v36, v35
	v_fma_f32 v38, -v34, v37, v36
	v_fmac_f32_e32 v37, v38, v35
	v_fma_f32 v34, -v34, v37, v36
	v_div_fmas_f32 v34, v34, v35, v37
	v_div_fixup_f32 v27, v34, v27, 1.0
	v_div_scale_f32 v34, s[22:23], v26, v26, 1.0
	v_rcp_f32_e32 v35, v34
	s_nop 0
	v_fma_f32 v36, -v34, v35, 1.0
	v_fmac_f32_e32 v35, v36, v35
	v_div_scale_f32 v36, vcc, 1.0, v26, 1.0
	v_mul_f32_e32 v37, v36, v35
	v_fma_f32 v38, -v34, v37, v36
	v_fmac_f32_e32 v37, v38, v35
	v_fma_f32 v34, -v34, v37, v36
	v_div_fmas_f32 v34, v34, v35, v37
	v_div_fixup_f32 v26, v34, v26, 1.0
	v_div_scale_f32 v34, s[22:23], v33, v33, 1.0
	v_rcp_f32_e32 v35, v34
	s_nop 0
	v_fma_f32 v36, -v34, v35, 1.0
	v_fmac_f32_e32 v35, v36, v35
	v_div_scale_f32 v36, vcc, 1.0, v33, 1.0
	v_mul_f32_e32 v37, v36, v35
	v_fma_f32 v38, -v34, v37, v36
	v_fmac_f32_e32 v37, v38, v35
	v_fma_f32 v34, -v34, v37, v36
	v_div_fmas_f32 v34, v34, v35, v37
	v_div_fixup_f32 v33, v34, v33, 1.0
	v_div_scale_f32 v34, s[22:23], v32, v32, 1.0
	v_rcp_f32_e32 v35, v34
	s_nop 0
	v_fma_f32 v36, -v34, v35, 1.0
	v_fmac_f32_e32 v35, v36, v35
	v_div_scale_f32 v36, vcc, 1.0, v32, 1.0
	v_mul_f32_e32 v37, v36, v35
	v_fma_f32 v38, -v34, v37, v36
	v_fmac_f32_e32 v37, v38, v35
	v_fma_f32 v34, -v34, v37, v36
	v_div_fmas_f32 v34, v34, v35, v37
	v_div_fixup_f32 v32, v34, v32, 1.0
.LBB0_666:
	s_or_b64 exec, exec, s[4:5]
	v_cvt_pk_f16_f32 v32, v32, v33
	v_cvt_pk_f16_f32 v33, v26, v27
	v_pk_mul_f32 v[22:23], v[24:25], v[22:23]
	v_pk_mul_f32 v[24:25], v[72:73], v[20:21]
	v_mov_b32_e32 v226, v32
	v_mov_b32_e32 v227, v33
	v_and_b32_e32 v236, 16, v148
	v_lshrrev_b32_e32 v237, 1, v236
	v_add_u32_e32 v236, v236, v237
	v_mov_b32_e32 v237, 0
	v_lshl_add_u64 v[236:237], v[236:237], 0, v[30:31]
	v_permlane16_swap_b32_e32 v224, v226
	v_permlane16_swap_b32_e32 v225, v227
	global_store_dwordx4 v[236:237], v[224:227], off offset:64
	s_and_saveexec_b64 s[4:5], s[20:21]
	s_cbranch_execz .LBB0_668
	v_mul_f32_e32 v22, 0xbfb8aa3b, v22
	v_mul_f32_e32 v23, 0xbfb8aa3b, v23
	v_exp_f32_e32 v22, v22
	v_exp_f32_e32 v23, v23
	v_mul_f32_e32 v20, 0xbfb8aa3b, v24
	v_mul_f32_e32 v21, 0xbfb8aa3b, v25
	v_exp_f32_e32 v20, v20
	v_pk_add_f32 v[22:23], v[22:23], 1.0 op_sel_hi:[1,0]
	v_exp_f32_e32 v21, v21
	v_div_scale_f32 v24, s[22:23], v23, v23, 1.0
	v_rcp_f32_e32 v25, v24
	v_pk_add_f32 v[20:21], v[20:21], 1.0 op_sel_hi:[1,0]
	v_fma_f32 v26, -v24, v25, 1.0
	v_fmac_f32_e32 v25, v26, v25
	v_div_scale_f32 v26, vcc, 1.0, v23, 1.0
	v_mul_f32_e32 v27, v26, v25
	v_fma_f32 v30, -v24, v27, v26
	v_fmac_f32_e32 v27, v30, v25
	v_fma_f32 v24, -v24, v27, v26
	v_div_fmas_f32 v24, v24, v25, v27
	v_div_fixup_f32 v23, v24, v23, 1.0
	v_div_scale_f32 v24, s[22:23], v22, v22, 1.0
	v_rcp_f32_e32 v25, v24
	s_nop 0
	v_fma_f32 v26, -v24, v25, 1.0
	v_fmac_f32_e32 v25, v26, v25
	v_div_scale_f32 v26, vcc, 1.0, v22, 1.0
	v_mul_f32_e32 v27, v26, v25
	v_fma_f32 v30, -v24, v27, v26
	v_fmac_f32_e32 v27, v30, v25
	v_fma_f32 v24, -v24, v27, v26
	v_div_fmas_f32 v24, v24, v25, v27
	v_div_fixup_f32 v22, v24, v22, 1.0
	v_div_scale_f32 v24, s[22:23], v21, v21, 1.0
	v_rcp_f32_e32 v25, v24
	s_nop 0
	v_fma_f32 v26, -v24, v25, 1.0
	v_fmac_f32_e32 v25, v26, v25
	v_div_scale_f32 v26, vcc, 1.0, v21, 1.0
	v_mul_f32_e32 v27, v26, v25
	v_fma_f32 v30, -v24, v27, v26
	v_fmac_f32_e32 v27, v30, v25
	v_fma_f32 v24, -v24, v27, v26
	v_div_fmas_f32 v24, v24, v25, v27
	v_div_fixup_f32 v25, v24, v21, 1.0
	v_div_scale_f32 v21, s[22:23], v20, v20, 1.0
	v_rcp_f32_e32 v24, v21
	s_nop 0
	v_fma_f32 v26, -v21, v24, 1.0
	v_fmac_f32_e32 v24, v26, v24
	v_div_scale_f32 v26, vcc, 1.0, v20, 1.0
	v_mul_f32_e32 v27, v26, v24
	v_fma_f32 v30, -v21, v27, v26
	v_fmac_f32_e32 v27, v30, v24
	v_fma_f32 v21, -v21, v27, v26
	v_div_fmas_f32 v21, v21, v24, v27
	v_div_fixup_f32 v24, v21, v20, 1.0
; DI unsigned pack2(float lo, float hi) { f2_t v = {lo, hi}; h2_t b = __builtin_convertvector(v, h2_t); return __builtin_bit_cast(unsigned, b); }
; DI float sigmoidf_(float x) { return 1.0f / (1.0f + __expf(-x)); }
; DI void phase_proj(const Params& P, int l, char* smem) {
;     ...
; #pragma unroll
;       for (int mt = 0; mt < 4; ++mt) {
;         const int row = row0 + mt * 16 + lr;
; #pragma unroll
;         for (int nt = 0; nt < 4; ++nt) {
;           f32x4 v = acc[mt][nt] * sc;
;           if (sig) { v[0] = sigmoidf_(v[0]); v[1] = sigmoidf_(v[1]); v[2] = sigmoidf_(v[2]); v[3] = sigmoidf_(v[3]); }
;           *(uint2*)(Pb + (size_t)row * PW + col0 + nt * 16 + 4 * g) = make_uint2(pack2(v[0], v[1]), pack2(v[2], v[3]));
;         }
;       }
.LBB0_668:
	s_or_b64 exec, exec, s[4:5]
	v_cvt_pk_f16_f32 v24, v24, v25
	v_cvt_pk_f16_f32 v25, v22, v23
	v_mov_b32_e32 v22, v72
	v_mov_b32_e32 v23, v72
	v_mad_i64_i32 v[20:21], s[4:5], v68, s0, v[28:29]
	v_pk_mul_f32 v[18:19], v[22:23], v[18:19]
	v_pk_mul_f32 v[16:17], v[72:73], v[16:17]
	v_mov_b32_e32 v228, v24
	v_mov_b32_e32 v229, v25
	s_and_saveexec_b64 s[4:5], s[20:21]
	s_cbranch_execz .LBB0_670
	v_mul_f32_e32 v18, 0xbfb8aa3b, v18
	v_mul_f32_e32 v19, 0xbfb8aa3b, v19
	v_exp_f32_e32 v18, v18
	v_exp_f32_e32 v19, v19
	v_mul_f32_e32 v16, 0xbfb8aa3b, v16
	v_mul_f32_e32 v17, 0xbfb8aa3b, v17
	v_exp_f32_e32 v16, v16
	v_pk_add_f32 v[18:19], v[18:19], 1.0 op_sel_hi:[1,0]
	v_exp_f32_e32 v17, v17
	v_div_scale_f32 v24, s[22:23], v19, v19, 1.0
	v_rcp_f32_e32 v25, v24
	v_pk_add_f32 v[16:17], v[16:17], 1.0 op_sel_hi:[1,0]
	v_fma_f32 v26, -v24, v25, 1.0
	v_fmac_f32_e32 v25, v26, v25
	v_div_scale_f32 v26, vcc, 1.0, v19, 1.0
	v_mul_f32_e32 v27, v26, v25
	v_fma_f32 v30, -v24, v27, v26
	v_fmac_f32_e32 v27, v30, v25
	v_fma_f32 v24, -v24, v27, v26
	v_div_fmas_f32 v24, v24, v25, v27
	v_div_fixup_f32 v19, v24, v19, 1.0
	v_div_scale_f32 v24, s[22:23], v18, v18, 1.0
	v_rcp_f32_e32 v25, v24
	s_nop 0
	v_fma_f32 v26, -v24, v25, 1.0
	v_fmac_f32_e32 v25, v26, v25
	v_div_scale_f32 v26, vcc, 1.0, v18, 1.0
	v_mul_f32_e32 v27, v26, v25
	v_fma_f32 v30, -v24, v27, v26
	v_fmac_f32_e32 v27, v30, v25
	v_fma_f32 v24, -v24, v27, v26
	v_div_fmas_f32 v24, v24, v25, v27
	v_div_fixup_f32 v18, v24, v18, 1.0
	v_div_scale_f32 v24, s[22:23], v17, v17, 1.0
	v_rcp_f32_e32 v25, v24
	s_nop 0
	v_fma_f32 v26, -v24, v25, 1.0
	v_fmac_f32_e32 v25, v26, v25
	v_div_scale_f32 v26, vcc, 1.0, v17, 1.0
	v_mul_f32_e32 v27, v26, v25
	v_fma_f32 v30, -v24, v27, v26
	v_fmac_f32_e32 v27, v30, v25
	v_fma_f32 v24, -v24, v27, v26
	v_div_fmas_f32 v24, v24, v25, v27
	v_div_fixup_f32 v17, v24, v17, 1.0
	v_div_scale_f32 v24, s[22:23], v16, v16, 1.0
	v_rcp_f32_e32 v25, v24
	s_nop 0
	v_fma_f32 v26, -v24, v25, 1.0
	v_fmac_f32_e32 v25, v26, v25
	v_div_scale_f32 v26, vcc, 1.0, v16, 1.0
	v_mul_f32_e32 v27, v26, v25
	v_fma_f32 v30, -v24, v27, v26
	v_fmac_f32_e32 v27, v30, v25
	v_fma_f32 v24, -v24, v27, v26
	v_div_fmas_f32 v24, v24, v25, v27
	v_div_fixup_f32 v16, v24, v16, 1.0
.LBB0_670:
	s_or_b64 exec, exec, s[4:5]
	v_cvt_pk_f16_f32 v16, v16, v17
	v_cvt_pk_f16_f32 v17, v18, v19
	v_mov_b32_e32 v230, v16
	v_mov_b32_e32 v231, v17
	v_and_b32_e32 v236, 16, v148
	v_lshrrev_b32_e32 v237, 1, v236
	v_add_u32_e32 v236, v236, v237
	v_mov_b32_e32 v237, 0
	v_lshl_add_u64 v[236:237], v[236:237], 0, v[20:21]
	v_permlane16_swap_b32_e32 v228, v230
	v_permlane16_swap_b32_e32 v229, v231
	global_store_dwordx4 v[236:237], v[228:231], off
	v_pk_mul_f32 v[16:17], v[22:23], v[112:113]
	v_pk_mul_f32 v[18:19], v[72:73], v[110:111]
	s_and_saveexec_b64 s[4:5], s[20:21]
	s_cbranch_execz .LBB0_672
	v_mul_f32_e32 v16, 0xbfb8aa3b, v16
	v_mul_f32_e32 v17, 0xbfb8aa3b, v17
	v_exp_f32_e32 v16, v16
	v_exp_f32_e32 v17, v17
	v_mul_f32_e32 v18, 0xbfb8aa3b, v18
	v_mul_f32_e32 v19, 0xbfb8aa3b, v19
	v_exp_f32_e32 v18, v18
	v_pk_add_f32 v[16:17], v[16:17], 1.0 op_sel_hi:[1,0]
	v_exp_f32_e32 v19, v19
	v_div_scale_f32 v22, s[22:23], v17, v17, 1.0
	v_rcp_f32_e32 v23, v22
	v_pk_add_f32 v[18:19], v[18:19], 1.0 op_sel_hi:[1,0]
	v_fma_f32 v24, -v22, v23, 1.0
	v_fmac_f32_e32 v23, v24, v23
	v_div_scale_f32 v24, vcc, 1.0, v17, 1.0
	v_mul_f32_e32 v25, v24, v23
	v_fma_f32 v26, -v22, v25, v24
	v_fmac_f32_e32 v25, v26, v23
	v_fma_f32 v22, -v22, v25, v24
	v_div_fmas_f32 v22, v22, v23, v25
	v_div_fixup_f32 v17, v22, v17, 1.0
	v_div_scale_f32 v22, s[22:23], v16, v16, 1.0
	v_rcp_f32_e32 v23, v22
	s_nop 0
	v_fma_f32 v24, -v22, v23, 1.0
	v_fmac_f32_e32 v23, v24, v23
	v_div_scale_f32 v24, vcc, 1.0, v16, 1.0
	v_mul_f32_e32 v25, v24, v23
	v_fma_f32 v26, -v22, v25, v24
	v_fmac_f32_e32 v25, v26, v23
	v_fma_f32 v22, -v22, v25, v24
	v_div_fmas_f32 v22, v22, v23, v25
	v_div_fixup_f32 v16, v22, v16, 1.0
	v_div_scale_f32 v22, s[22:23], v19, v19, 1.0
	v_rcp_f32_e32 v23, v22
	s_nop 0
	v_fma_f32 v24, -v22, v23, 1.0
	v_fmac_f32_e32 v23, v24, v23
	v_div_scale_f32 v24, vcc, 1.0, v19, 1.0
	v_mul_f32_e32 v25, v24, v23
	v_fma_f32 v26, -v22, v25, v24
	v_fmac_f32_e32 v25, v26, v23
	v_fma_f32 v22, -v22, v25, v24
	v_div_fmas_f32 v22, v22, v23, v25
	v_div_fixup_f32 v19, v22, v19, 1.0
	v_div_scale_f32 v22, s[22:23], v18, v18, 1.0
	v_rcp_f32_e32 v23, v22
	s_nop 0
	v_fma_f32 v24, -v22, v23, 1.0
	v_fmac_f32_e32 v23, v24, v23
	v_div_scale_f32 v24, vcc, 1.0, v18, 1.0
	v_mul_f32_e32 v25, v24, v23
	v_fma_f32 v26, -v22, v25, v24
	v_fmac_f32_e32 v25, v26, v23
	v_fma_f32 v22, -v22, v25, v24
	v_div_fmas_f32 v22, v22, v23, v25
	v_div_fixup_f32 v18, v22, v18, 1.0
; DI unsigned pack2(float lo, float hi) { f2_t v = {lo, hi}; h2_t b = __builtin_convertvector(v, h2_t); return __builtin_bit_cast(unsigned, b); }
; DI float sigmoidf_(float x) { return 1.0f / (1.0f + __expf(-x)); }
; DI void phase_proj(const Params& P, int l, char* smem) {
;     ...
; #pragma unroll
;       for (int mt = 0; mt < 4; ++mt) {
;         const int row = row0 + mt * 16 + lr;
; #pragma unroll
;         for (int nt = 0; nt < 4; ++nt) {
;           f32x4 v = acc[mt][nt] * sc;
;           if (sig) { v[0] = sigmoidf_(v[0]); v[1] = sigmoidf_(v[1]); v[2] = sigmoidf_(v[2]); v[3] = sigmoidf_(v[3]); }
;           *(uint2*)(Pb + (size_t)row * PW + col0 + nt * 16 + 4 * g) = make_uint2(pack2(v[0], v[1]), pack2(v[2], v[3]));
;         }
;       }
.LBB0_672:
	s_or_b64 exec, exec, s[4:5]
	v_cvt_pk_f16_f32 v18, v18, v19
	v_cvt_pk_f16_f32 v19, v16, v17
	v_mov_b32_e32 v16, v72
	v_mov_b32_e32 v17, v72
	v_mov_b32_e32 v232, v18
	v_mov_b32_e32 v233, v19
	v_pk_mul_f32 v[18:19], v[16:17], v[108:109]
	v_pk_mul_f32 v[22:23], v[72:73], v[106:107]
	s_and_saveexec_b64 s[4:5], s[20:21]
	s_cbranch_execz .LBB0_674
	v_mul_f32_e32 v18, 0xbfb8aa3b, v18
	v_mul_f32_e32 v19, 0xbfb8aa3b, v19
	v_exp_f32_e32 v18, v18
	v_exp_f32_e32 v19, v19
	v_mul_f32_e32 v22, 0xbfb8aa3b, v22
	v_mul_f32_e32 v23, 0xbfb8aa3b, v23
	v_exp_f32_e32 v22, v22
	v_pk_add_f32 v[18:19], v[18:19], 1.0 op_sel_hi:[1,0]
	v_exp_f32_e32 v23, v23
	v_div_scale_f32 v24, s[22:23], v19, v19, 1.0
	v_rcp_f32_e32 v25, v24
	v_pk_add_f32 v[22:23], v[22:23], 1.0 op_sel_hi:[1,0]
	v_fma_f32 v26, -v24, v25, 1.0
	v_fmac_f32_e32 v25, v26, v25
	v_div_scale_f32 v26, vcc, 1.0, v19, 1.0
	v_mul_f32_e32 v27, v26, v25
	v_fma_f32 v30, -v24, v27, v26
	v_fmac_f32_e32 v27, v30, v25
	v_fma_f32 v24, -v24, v27, v26
	v_div_fmas_f32 v24, v24, v25, v27
	v_div_fixup_f32 v19, v24, v19, 1.0
	v_div_scale_f32 v24, s[22:23], v18, v18, 1.0
	v_rcp_f32_e32 v25, v24
	s_nop 0
	v_fma_f32 v26, -v24, v25, 1.0
	v_fmac_f32_e32 v25, v26, v25
	v_div_scale_f32 v26, vcc, 1.0, v18, 1.0
	v_mul_f32_e32 v27, v26, v25
	v_fma_f32 v30, -v24, v27, v26
	v_fmac_f32_e32 v27, v30, v25
	v_fma_f32 v24, -v24, v27, v26
	v_div_fmas_f32 v24, v24, v25, v27
	v_div_fixup_f32 v18, v24, v18, 1.0
	v_div_scale_f32 v24, s[22:23], v23, v23, 1.0
	v_rcp_f32_e32 v25, v24
	s_nop 0
	v_fma_f32 v26, -v24, v25, 1.0
	v_fmac_f32_e32 v25, v26, v25
	v_div_scale_f32 v26, vcc, 1.0, v23, 1.0
	v_mul_f32_e32 v27, v26, v25
	v_fma_f32 v30, -v24, v27, v26
	v_fmac_f32_e32 v27, v30, v25
	v_fma_f32 v24, -v24, v27, v26
	v_div_fmas_f32 v24, v24, v25, v27
	v_div_fixup_f32 v23, v24, v23, 1.0
	v_div_scale_f32 v24, s[22:23], v22, v22, 1.0
	v_rcp_f32_e32 v25, v24
	s_nop 0
	v_fma_f32 v26, -v24, v25, 1.0
	v_fmac_f32_e32 v25, v26, v25
	v_div_scale_f32 v26, vcc, 1.0, v22, 1.0
	v_mul_f32_e32 v27, v26, v25
	v_fma_f32 v30, -v24, v27, v26
	v_fmac_f32_e32 v27, v30, v25
	v_fma_f32 v24, -v24, v27, v26
	v_div_fmas_f32 v24, v24, v25, v27
	v_div_fixup_f32 v22, v24, v22, 1.0
.LBB0_674:
	s_or_b64 exec, exec, s[4:5]
	v_cvt_pk_f16_f32 v22, v22, v23
	v_cvt_pk_f16_f32 v23, v18, v19
	v_pk_mul_f32 v[14:15], v[16:17], v[14:15]
	v_pk_mul_f32 v[16:17], v[72:73], v[12:13]
	v_mov_b32_e32 v234, v22
	v_mov_b32_e32 v235, v23
	v_and_b32_e32 v236, 16, v148
	v_lshrrev_b32_e32 v237, 1, v236
	v_add_u32_e32 v236, v236, v237
	v_mov_b32_e32 v237, 0
	v_lshl_add_u64 v[236:237], v[236:237], 0, v[20:21]
	v_permlane16_swap_b32_e32 v232, v234
	v_permlane16_swap_b32_e32 v233, v235
	global_store_dwordx4 v[236:237], v[232:235], off offset:64
	s_and_saveexec_b64 s[4:5], s[20:21]
	s_cbranch_execz .LBB0_676
	v_mul_f32_e32 v14, 0xbfb8aa3b, v14
	v_mul_f32_e32 v15, 0xbfb8aa3b, v15
	v_exp_f32_e32 v14, v14
	v_exp_f32_e32 v15, v15
	v_mul_f32_e32 v12, 0xbfb8aa3b, v16
	v_mul_f32_e32 v13, 0xbfb8aa3b, v17
	v_exp_f32_e32 v12, v12
	v_pk_add_f32 v[14:15], v[14:15], 1.0 op_sel_hi:[1,0]
	v_exp_f32_e32 v13, v13
	v_div_scale_f32 v16, s[22:23], v15, v15, 1.0
	v_rcp_f32_e32 v17, v16
	v_pk_add_f32 v[12:13], v[12:13], 1.0 op_sel_hi:[1,0]
	v_fma_f32 v18, -v16, v17, 1.0
	v_fmac_f32_e32 v17, v18, v17
	v_div_scale_f32 v18, vcc, 1.0, v15, 1.0
	v_mul_f32_e32 v19, v18, v17
	v_fma_f32 v20, -v16, v19, v18
	v_fmac_f32_e32 v19, v20, v17
	v_fma_f32 v16, -v16, v19, v18
	v_div_fmas_f32 v16, v16, v17, v19
	v_div_fixup_f32 v15, v16, v15, 1.0
	v_div_scale_f32 v16, s[22:23], v14, v14, 1.0
	v_rcp_f32_e32 v17, v16
	s_nop 0
	v_fma_f32 v18, -v16, v17, 1.0
	v_fmac_f32_e32 v17, v18, v17
	v_div_scale_f32 v18, vcc, 1.0, v14, 1.0
	v_mul_f32_e32 v19, v18, v17
	v_fma_f32 v20, -v16, v19, v18
	v_fmac_f32_e32 v19, v20, v17
	v_fma_f32 v16, -v16, v19, v18
	v_div_fmas_f32 v16, v16, v17, v19
	v_div_fixup_f32 v14, v16, v14, 1.0
	v_div_scale_f32 v16, s[22:23], v13, v13, 1.0
	v_rcp_f32_e32 v17, v16
	s_nop 0
	v_fma_f32 v18, -v16, v17, 1.0
	v_fmac_f32_e32 v17, v18, v17
	v_div_scale_f32 v18, vcc, 1.0, v13, 1.0
	v_mul_f32_e32 v19, v18, v17
	v_fma_f32 v20, -v16, v19, v18
	v_fmac_f32_e32 v19, v20, v17
	v_fma_f32 v16, -v16, v19, v18
	v_div_fmas_f32 v16, v16, v17, v19
	v_div_fixup_f32 v17, v16, v13, 1.0
	v_div_scale_f32 v13, s[22:23], v12, v12, 1.0
	v_rcp_f32_e32 v16, v13
	s_nop 0
	v_fma_f32 v18, -v13, v16, 1.0
	v_fmac_f32_e32 v16, v18, v16
	v_div_scale_f32 v18, vcc, 1.0, v12, 1.0
	v_mul_f32_e32 v19, v18, v16
	v_fma_f32 v20, -v13, v19, v18
	v_fmac_f32_e32 v19, v20, v16
	v_fma_f32 v13, -v13, v19, v18
	v_div_fmas_f32 v13, v13, v16, v19
	v_div_fixup_f32 v16, v13, v12, 1.0
; DI unsigned pack2(float lo, float hi) { f2_t v = {lo, hi}; h2_t b = __builtin_convertvector(v, h2_t); return __builtin_bit_cast(unsigned, b); }
; DI float sigmoidf_(float x) { return 1.0f / (1.0f + __expf(-x)); }
; DI void phase_proj(const Params& P, int l, char* smem) {
;     ...
; #pragma unroll
;       for (int mt = 0; mt < 4; ++mt) {
;         const int row = row0 + mt * 16 + lr;
; #pragma unroll
;         for (int nt = 0; nt < 4; ++nt) {
;           f32x4 v = acc[mt][nt] * sc;
;           if (sig) { v[0] = sigmoidf_(v[0]); v[1] = sigmoidf_(v[1]); v[2] = sigmoidf_(v[2]); v[3] = sigmoidf_(v[3]); }
;           *(uint2*)(Pb + (size_t)row * PW + col0 + nt * 16 + 4 * g) = make_uint2(pack2(v[0], v[1]), pack2(v[2], v[3]));
;         }
;       }
.LBB0_676:
	s_or_b64 exec, exec, s[4:5]
	v_cvt_pk_f16_f32 v16, v16, v17
	v_cvt_pk_f16_f32 v17, v14, v15
	v_mov_b32_e32 v14, v72
	v_mov_b32_e32 v15, v72
	v_mad_i64_i32 v[12:13], s[4:5], v66, s0, v[28:29]
	v_pk_mul_f32 v[10:11], v[14:15], v[10:11]
	v_pk_mul_f32 v[8:9], v[72:73], v[8:9]
	v_mov_b32_e32 v220, v16
	v_mov_b32_e32 v221, v17
	s_and_saveexec_b64 s[4:5], s[20:21]
	s_cbranch_execz .LBB0_678
	v_mul_f32_e32 v10, 0xbfb8aa3b, v10
	v_mul_f32_e32 v11, 0xbfb8aa3b, v11
	v_exp_f32_e32 v10, v10
	v_exp_f32_e32 v11, v11
	v_mul_f32_e32 v8, 0xbfb8aa3b, v8
	v_mul_f32_e32 v9, 0xbfb8aa3b, v9
	v_exp_f32_e32 v8, v8
	v_pk_add_f32 v[10:11], v[10:11], 1.0 op_sel_hi:[1,0]
	v_exp_f32_e32 v9, v9
	v_div_scale_f32 v16, s[22:23], v11, v11, 1.0
	v_rcp_f32_e32 v17, v16
	v_pk_add_f32 v[8:9], v[8:9], 1.0 op_sel_hi:[1,0]
	v_fma_f32 v18, -v16, v17, 1.0
	v_fmac_f32_e32 v17, v18, v17
	v_div_scale_f32 v18, vcc, 1.0, v11, 1.0
	v_mul_f32_e32 v19, v18, v17
	v_fma_f32 v20, -v16, v19, v18
	v_fmac_f32_e32 v19, v20, v17
	v_fma_f32 v16, -v16, v19, v18
	v_div_fmas_f32 v16, v16, v17, v19
	v_div_fixup_f32 v11, v16, v11, 1.0
	v_div_scale_f32 v16, s[22:23], v10, v10, 1.0
	v_rcp_f32_e32 v17, v16
	s_nop 0
	v_fma_f32 v18, -v16, v17, 1.0
	v_fmac_f32_e32 v17, v18, v17
	v_div_scale_f32 v18, vcc, 1.0, v10, 1.0
	v_mul_f32_e32 v19, v18, v17
	v_fma_f32 v20, -v16, v19, v18
	v_fmac_f32_e32 v19, v20, v17
	v_fma_f32 v16, -v16, v19, v18
	v_div_fmas_f32 v16, v16, v17, v19
	v_div_fixup_f32 v10, v16, v10, 1.0
	v_div_scale_f32 v16, s[22:23], v9, v9, 1.0
	v_rcp_f32_e32 v17, v16
	s_nop 0
	v_fma_f32 v18, -v16, v17, 1.0
	v_fmac_f32_e32 v17, v18, v17
	v_div_scale_f32 v18, vcc, 1.0, v9, 1.0
	v_mul_f32_e32 v19, v18, v17
	v_fma_f32 v20, -v16, v19, v18
	v_fmac_f32_e32 v19, v20, v17
	v_fma_f32 v16, -v16, v19, v18
	v_div_fmas_f32 v16, v16, v17, v19
	v_div_fixup_f32 v9, v16, v9, 1.0
	v_div_scale_f32 v16, s[22:23], v8, v8, 1.0
	v_rcp_f32_e32 v17, v16
	s_nop 0
	v_fma_f32 v18, -v16, v17, 1.0
	v_fmac_f32_e32 v17, v18, v17
	v_div_scale_f32 v18, vcc, 1.0, v8, 1.0
	v_mul_f32_e32 v19, v18, v17
	v_fma_f32 v20, -v16, v19, v18
	v_fmac_f32_e32 v19, v20, v17
	v_fma_f32 v16, -v16, v19, v18
	v_div_fmas_f32 v16, v16, v17, v19
	v_div_fixup_f32 v8, v16, v8, 1.0
.LBB0_678:
	s_or_b64 exec, exec, s[4:5]
	v_cvt_pk_f16_f32 v8, v8, v9
	v_cvt_pk_f16_f32 v9, v10, v11
	v_mov_b32_e32 v222, v8
	v_mov_b32_e32 v223, v9
	v_and_b32_e32 v236, 16, v148
	v_lshrrev_b32_e32 v237, 1, v236
	v_add_u32_e32 v236, v236, v237
	v_mov_b32_e32 v237, 0
	v_lshl_add_u64 v[236:237], v[236:237], 0, v[12:13]
	v_permlane16_swap_b32_e32 v220, v222
	v_permlane16_swap_b32_e32 v221, v223
	global_store_dwordx4 v[236:237], v[220:223], off
	v_pk_mul_f32 v[8:9], v[14:15], v[104:105]
	v_pk_mul_f32 v[10:11], v[72:73], v[82:83]
	s_and_saveexec_b64 s[4:5], s[20:21]
	s_cbranch_execz .LBB0_680
	v_mul_f32_e32 v8, 0xbfb8aa3b, v8
	v_mul_f32_e32 v9, 0xbfb8aa3b, v9
	v_exp_f32_e32 v8, v8
	v_exp_f32_e32 v9, v9
	v_mul_f32_e32 v10, 0xbfb8aa3b, v10
	v_mul_f32_e32 v11, 0xbfb8aa3b, v11
	v_exp_f32_e32 v10, v10
	v_pk_add_f32 v[8:9], v[8:9], 1.0 op_sel_hi:[1,0]
	v_exp_f32_e32 v11, v11
	v_div_scale_f32 v14, s[22:23], v9, v9, 1.0
	v_rcp_f32_e32 v15, v14
	v_pk_add_f32 v[10:11], v[10:11], 1.0 op_sel_hi:[1,0]
	v_fma_f32 v16, -v14, v15, 1.0
	v_fmac_f32_e32 v15, v16, v15
	v_div_scale_f32 v16, vcc, 1.0, v9, 1.0
	v_mul_f32_e32 v17, v16, v15
	v_fma_f32 v18, -v14, v17, v16
	v_fmac_f32_e32 v17, v18, v15
	v_fma_f32 v14, -v14, v17, v16
	v_div_fmas_f32 v14, v14, v15, v17
	v_div_fixup_f32 v9, v14, v9, 1.0
	v_div_scale_f32 v14, s[22:23], v8, v8, 1.0
	v_rcp_f32_e32 v15, v14
	s_nop 0
	v_fma_f32 v16, -v14, v15, 1.0
	v_fmac_f32_e32 v15, v16, v15
	v_div_scale_f32 v16, vcc, 1.0, v8, 1.0
	v_mul_f32_e32 v17, v16, v15
	v_fma_f32 v18, -v14, v17, v16
	v_fmac_f32_e32 v17, v18, v15
	v_fma_f32 v14, -v14, v17, v16
	v_div_fmas_f32 v14, v14, v15, v17
	v_div_fixup_f32 v8, v14, v8, 1.0
	v_div_scale_f32 v14, s[22:23], v11, v11, 1.0
	v_rcp_f32_e32 v15, v14
	s_nop 0
	v_fma_f32 v16, -v14, v15, 1.0
	v_fmac_f32_e32 v15, v16, v15
	v_div_scale_f32 v16, vcc, 1.0, v11, 1.0
	v_mul_f32_e32 v17, v16, v15
	v_fma_f32 v18, -v14, v17, v16
	v_fmac_f32_e32 v17, v18, v15
	v_fma_f32 v14, -v14, v17, v16
	v_div_fmas_f32 v14, v14, v15, v17
	v_div_fixup_f32 v11, v14, v11, 1.0
	v_div_scale_f32 v14, s[22:23], v10, v10, 1.0
	v_rcp_f32_e32 v15, v14
	s_nop 0
	v_fma_f32 v16, -v14, v15, 1.0
	v_fmac_f32_e32 v15, v16, v15
	v_div_scale_f32 v16, vcc, 1.0, v10, 1.0
	v_mul_f32_e32 v17, v16, v15
	v_fma_f32 v18, -v14, v17, v16
	v_fmac_f32_e32 v17, v18, v15
	v_fma_f32 v14, -v14, v17, v16
	v_div_fmas_f32 v14, v14, v15, v17
	v_div_fixup_f32 v10, v14, v10, 1.0
; DI unsigned pack2(float lo, float hi) { f2_t v = {lo, hi}; h2_t b = __builtin_convertvector(v, h2_t); return __builtin_bit_cast(unsigned, b); }
; DI float sigmoidf_(float x) { return 1.0f / (1.0f + __expf(-x)); }
; DI void phase_proj(const Params& P, int l, char* smem) {
;     ...
; #pragma unroll
;       for (int mt = 0; mt < 4; ++mt) {
;         const int row = row0 + mt * 16 + lr;
; #pragma unroll
;         for (int nt = 0; nt < 4; ++nt) {
;           f32x4 v = acc[mt][nt] * sc;
;           if (sig) { v[0] = sigmoidf_(v[0]); v[1] = sigmoidf_(v[1]); v[2] = sigmoidf_(v[2]); v[3] = sigmoidf_(v[3]); }
;           *(uint2*)(Pb + (size_t)row * PW + col0 + nt * 16 + 4 * g) = make_uint2(pack2(v[0], v[1]), pack2(v[2], v[3]));
;         }
;       }
.LBB0_680:
	s_or_b64 exec, exec, s[4:5]
	v_cvt_pk_f16_f32 v10, v10, v11
	v_cvt_pk_f16_f32 v11, v8, v9
	v_mov_b32_e32 v8, v72
	v_mov_b32_e32 v9, v72
	v_mov_b32_e32 v224, v10
	v_mov_b32_e32 v225, v11
	v_pk_mul_f32 v[10:11], v[8:9], v[80:81]
	v_pk_mul_f32 v[14:15], v[72:73], v[78:79]
	s_and_saveexec_b64 s[4:5], s[20:21]
	s_cbranch_execz .LBB0_682
	v_mul_f32_e32 v10, 0xbfb8aa3b, v10
	v_mul_f32_e32 v11, 0xbfb8aa3b, v11
	v_exp_f32_e32 v10, v10
	v_exp_f32_e32 v11, v11
	v_mul_f32_e32 v14, 0xbfb8aa3b, v14
	v_mul_f32_e32 v15, 0xbfb8aa3b, v15
	v_exp_f32_e32 v14, v14
	v_pk_add_f32 v[10:11], v[10:11], 1.0 op_sel_hi:[1,0]
	v_exp_f32_e32 v15, v15
	v_div_scale_f32 v16, s[22:23], v11, v11, 1.0
	v_rcp_f32_e32 v17, v16
	v_pk_add_f32 v[14:15], v[14:15], 1.0 op_sel_hi:[1,0]
	v_fma_f32 v18, -v16, v17, 1.0
	v_fmac_f32_e32 v17, v18, v17
	v_div_scale_f32 v18, vcc, 1.0, v11, 1.0
	v_mul_f32_e32 v19, v18, v17
	v_fma_f32 v20, -v16, v19, v18
	v_fmac_f32_e32 v19, v20, v17
	v_fma_f32 v16, -v16, v19, v18
	v_div_fmas_f32 v16, v16, v17, v19
	v_div_fixup_f32 v11, v16, v11, 1.0
	v_div_scale_f32 v16, s[22:23], v10, v10, 1.0
	v_rcp_f32_e32 v17, v16
	s_nop 0
	v_fma_f32 v18, -v16, v17, 1.0
	v_fmac_f32_e32 v17, v18, v17
	v_div_scale_f32 v18, vcc, 1.0, v10, 1.0
	v_mul_f32_e32 v19, v18, v17
	v_fma_f32 v20, -v16, v19, v18
	v_fmac_f32_e32 v19, v20, v17
	v_fma_f32 v16, -v16, v19, v18
	v_div_fmas_f32 v16, v16, v17, v19
	v_div_fixup_f32 v10, v16, v10, 1.0
	v_div_scale_f32 v16, s[22:23], v15, v15, 1.0
	v_rcp_f32_e32 v17, v16
	s_nop 0
	v_fma_f32 v18, -v16, v17, 1.0
	v_fmac_f32_e32 v17, v18, v17
	v_div_scale_f32 v18, vcc, 1.0, v15, 1.0
	v_mul_f32_e32 v19, v18, v17
	v_fma_f32 v20, -v16, v19, v18
	v_fmac_f32_e32 v19, v20, v17
	v_fma_f32 v16, -v16, v19, v18
	v_div_fmas_f32 v16, v16, v17, v19
	v_div_fixup_f32 v15, v16, v15, 1.0
	v_div_scale_f32 v16, s[22:23], v14, v14, 1.0
	v_rcp_f32_e32 v17, v16
	s_nop 0
	v_fma_f32 v18, -v16, v17, 1.0
	v_fmac_f32_e32 v17, v18, v17
	v_div_scale_f32 v18, vcc, 1.0, v14, 1.0
	v_mul_f32_e32 v19, v18, v17
	v_fma_f32 v20, -v16, v19, v18
	v_fmac_f32_e32 v19, v20, v17
	v_fma_f32 v16, -v16, v19, v18
	v_div_fmas_f32 v16, v16, v17, v19
	v_div_fixup_f32 v14, v16, v14, 1.0
.LBB0_682:
	s_or_b64 exec, exec, s[4:5]
	v_cvt_pk_f16_f32 v14, v14, v15
	v_cvt_pk_f16_f32 v15, v10, v11
	v_pk_mul_f32 v[6:7], v[8:9], v[6:7]
	v_pk_mul_f32 v[8:9], v[72:73], v[4:5]
	v_mov_b32_e32 v226, v14
	v_mov_b32_e32 v227, v15
	v_and_b32_e32 v236, 16, v148
	v_lshrrev_b32_e32 v237, 1, v236
	v_add_u32_e32 v236, v236, v237
	v_mov_b32_e32 v237, 0
	v_lshl_add_u64 v[236:237], v[236:237], 0, v[12:13]
	v_permlane16_swap_b32_e32 v224, v226
	v_permlane16_swap_b32_e32 v225, v227
	global_store_dwordx4 v[236:237], v[224:227], off offset:64
	s_and_saveexec_b64 s[4:5], s[20:21]
	s_cbranch_execz .LBB0_684
	v_mul_f32_e32 v6, 0xbfb8aa3b, v6
	v_mul_f32_e32 v7, 0xbfb8aa3b, v7
	v_exp_f32_e32 v6, v6
	v_exp_f32_e32 v7, v7
	v_mul_f32_e32 v4, 0xbfb8aa3b, v8
	v_mul_f32_e32 v5, 0xbfb8aa3b, v9
	v_exp_f32_e32 v4, v4
	v_pk_add_f32 v[6:7], v[6:7], 1.0 op_sel_hi:[1,0]
	v_exp_f32_e32 v5, v5
	v_div_scale_f32 v8, s[22:23], v7, v7, 1.0
	v_rcp_f32_e32 v9, v8
	v_pk_add_f32 v[4:5], v[4:5], 1.0 op_sel_hi:[1,0]
	v_fma_f32 v10, -v8, v9, 1.0
	v_fmac_f32_e32 v9, v10, v9
	v_div_scale_f32 v10, vcc, 1.0, v7, 1.0
	v_mul_f32_e32 v11, v10, v9
	v_fma_f32 v12, -v8, v11, v10
	v_fmac_f32_e32 v11, v12, v9
	v_fma_f32 v8, -v8, v11, v10
	v_div_fmas_f32 v8, v8, v9, v11
	v_div_fixup_f32 v7, v8, v7, 1.0
	v_div_scale_f32 v8, s[22:23], v6, v6, 1.0
	v_rcp_f32_e32 v9, v8
	s_nop 0
	v_fma_f32 v10, -v8, v9, 1.0
	v_fmac_f32_e32 v9, v10, v9
	v_div_scale_f32 v10, vcc, 1.0, v6, 1.0
	v_mul_f32_e32 v11, v10, v9
	v_fma_f32 v12, -v8, v11, v10
	v_fmac_f32_e32 v11, v12, v9
	v_fma_f32 v8, -v8, v11, v10
	v_div_fmas_f32 v8, v8, v9, v11
	v_div_fixup_f32 v6, v8, v6, 1.0
	v_div_scale_f32 v8, s[22:23], v5, v5, 1.0
	v_rcp_f32_e32 v9, v8
	s_nop 0
	v_fma_f32 v10, -v8, v9, 1.0
	v_fmac_f32_e32 v9, v10, v9
	v_div_scale_f32 v10, vcc, 1.0, v5, 1.0
	v_mul_f32_e32 v11, v10, v9
	v_fma_f32 v12, -v8, v11, v10
	v_fmac_f32_e32 v11, v12, v9
	v_fma_f32 v8, -v8, v11, v10
	v_div_fmas_f32 v8, v8, v9, v11
	v_div_fixup_f32 v9, v8, v5, 1.0
	v_div_scale_f32 v5, s[22:23], v4, v4, 1.0
	v_rcp_f32_e32 v8, v5
	s_nop 0
	v_fma_f32 v10, -v5, v8, 1.0
	v_fmac_f32_e32 v8, v10, v8
	v_div_scale_f32 v10, vcc, 1.0, v4, 1.0
	v_mul_f32_e32 v11, v10, v8
	v_fma_f32 v12, -v5, v11, v10
	v_fmac_f32_e32 v11, v12, v8
	v_fma_f32 v5, -v5, v11, v10
	v_div_fmas_f32 v5, v5, v8, v11
	v_div_fixup_f32 v8, v5, v4, 1.0
.LBB0_684:
	s_or_b64 exec, exec, s[4:5]
	v_cvt_pk_f16_f32 v8, v8, v9
	v_cvt_pk_f16_f32 v9, v6, v7
	v_mov_b32_e32 v6, v72
	v_mov_b32_e32 v7, v72
	v_mad_i64_i32 v[4:5], s[4:5], v64, s0, v[28:29]
	v_pk_mul_f32 v[2:3], v[6:7], v[2:3]
	v_pk_mul_f32 v[0:1], v[72:73], v[0:1]
	v_mov_b32_e32 v228, v8
	v_mov_b32_e32 v229, v9
	s_and_saveexec_b64 s[4:5], s[20:21]
	s_cbranch_execz .LBB0_686
	v_mul_f32_e32 v2, 0xbfb8aa3b, v2
	v_mul_f32_e32 v3, 0xbfb8aa3b, v3
	v_exp_f32_e32 v2, v2
	v_exp_f32_e32 v3, v3
	v_mul_f32_e32 v0, 0xbfb8aa3b, v0
	v_mul_f32_e32 v1, 0xbfb8aa3b, v1
	v_exp_f32_e32 v0, v0
	v_pk_add_f32 v[2:3], v[2:3], 1.0 op_sel_hi:[1,0]
	v_exp_f32_e32 v1, v1
	v_div_scale_f32 v8, s[22:23], v3, v3, 1.0
	v_rcp_f32_e32 v9, v8
	v_pk_add_f32 v[0:1], v[0:1], 1.0 op_sel_hi:[1,0]
	v_fma_f32 v10, -v8, v9, 1.0
	v_fmac_f32_e32 v9, v10, v9
	v_div_scale_f32 v10, vcc, 1.0, v3, 1.0
	v_mul_f32_e32 v11, v10, v9
	v_fma_f32 v12, -v8, v11, v10
	v_fmac_f32_e32 v11, v12, v9
	v_fma_f32 v8, -v8, v11, v10
	v_div_fmas_f32 v8, v8, v9, v11
	v_div_fixup_f32 v3, v8, v3, 1.0
	v_div_scale_f32 v8, s[22:23], v2, v2, 1.0
	v_rcp_f32_e32 v9, v8
	s_nop 0
	v_fma_f32 v10, -v8, v9, 1.0
	v_fmac_f32_e32 v9, v10, v9
	v_div_scale_f32 v10, vcc, 1.0, v2, 1.0
	v_mul_f32_e32 v11, v10, v9
	v_fma_f32 v12, -v8, v11, v10
	v_fmac_f32_e32 v11, v12, v9
	v_fma_f32 v8, -v8, v11, v10
	v_div_fmas_f32 v8, v8, v9, v11
	v_div_fixup_f32 v2, v8, v2, 1.0
	v_div_scale_f32 v8, s[22:23], v1, v1, 1.0
	v_rcp_f32_e32 v9, v8
	s_nop 0
	v_fma_f32 v10, -v8, v9, 1.0
	v_fmac_f32_e32 v9, v10, v9
	v_div_scale_f32 v10, vcc, 1.0, v1, 1.0
	v_mul_f32_e32 v11, v10, v9
	v_fma_f32 v12, -v8, v11, v10
	v_fmac_f32_e32 v11, v12, v9
	v_fma_f32 v8, -v8, v11, v10
	v_div_fmas_f32 v8, v8, v9, v11
	v_div_fixup_f32 v1, v8, v1, 1.0
	v_div_scale_f32 v8, s[22:23], v0, v0, 1.0
	v_rcp_f32_e32 v9, v8
	s_nop 0
	v_fma_f32 v10, -v8, v9, 1.0
	v_fmac_f32_e32 v9, v10, v9
	v_div_scale_f32 v10, vcc, 1.0, v0, 1.0
	v_mul_f32_e32 v11, v10, v9
	v_fma_f32 v12, -v8, v11, v10
	v_fmac_f32_e32 v11, v12, v9
	v_fma_f32 v8, -v8, v11, v10
	v_div_fmas_f32 v8, v8, v9, v11
	v_div_fixup_f32 v0, v8, v0, 1.0
; DI unsigned pack2(float lo, float hi) { f2_t v = {lo, hi}; h2_t b = __builtin_convertvector(v, h2_t); return __builtin_bit_cast(unsigned, b); }
; DI float sigmoidf_(float x) { return 1.0f / (1.0f + __expf(-x)); }
; DI void phase_proj(const Params& P, int l, char* smem) {
;     ...
; #pragma unroll
;       for (int mt = 0; mt < 4; ++mt) {
;         const int row = row0 + mt * 16 + lr;
; #pragma unroll
;         for (int nt = 0; nt < 4; ++nt) {
;           f32x4 v = acc[mt][nt] * sc;
;           if (sig) { v[0] = sigmoidf_(v[0]); v[1] = sigmoidf_(v[1]); v[2] = sigmoidf_(v[2]); v[3] = sigmoidf_(v[3]); }
;           *(uint2*)(Pb + (size_t)row * PW + col0 + nt * 16 + 4 * g) = make_uint2(pack2(v[0], v[1]), pack2(v[2], v[3]));
;         }
;       }
.LBB0_686:
	s_or_b64 exec, exec, s[4:5]
	v_cvt_pk_f16_f32 v0, v0, v1
	v_cvt_pk_f16_f32 v1, v2, v3
	v_mov_b32_e32 v230, v0
	v_mov_b32_e32 v231, v1
	v_and_b32_e32 v236, 16, v148
	v_lshrrev_b32_e32 v237, 1, v236
	v_add_u32_e32 v236, v236, v237
	v_mov_b32_e32 v237, 0
	v_lshl_add_u64 v[236:237], v[236:237], 0, v[4:5]
	v_permlane16_swap_b32_e32 v228, v230
	v_permlane16_swap_b32_e32 v229, v231
	global_store_dwordx4 v[236:237], v[228:231], off
	v_pk_mul_f32 v[0:1], v[6:7], v[76:77]
	v_pk_mul_f32 v[2:3], v[72:73], v[74:75]
	s_and_saveexec_b64 s[4:5], s[20:21]
	s_cbranch_execz .LBB0_688
	v_mul_f32_e32 v0, 0xbfb8aa3b, v0
	v_mul_f32_e32 v1, 0xbfb8aa3b, v1
	v_exp_f32_e32 v0, v0
	v_exp_f32_e32 v1, v1
	v_mul_f32_e32 v2, 0xbfb8aa3b, v2
	v_mul_f32_e32 v3, 0xbfb8aa3b, v3
	v_exp_f32_e32 v2, v2
	v_pk_add_f32 v[0:1], v[0:1], 1.0 op_sel_hi:[1,0]
	v_exp_f32_e32 v3, v3
	v_div_scale_f32 v6, s[22:23], v1, v1, 1.0
	v_rcp_f32_e32 v7, v6
	v_pk_add_f32 v[2:3], v[2:3], 1.0 op_sel_hi:[1,0]
	v_fma_f32 v8, -v6, v7, 1.0
	v_fmac_f32_e32 v7, v8, v7
	v_div_scale_f32 v8, vcc, 1.0, v1, 1.0
	v_mul_f32_e32 v9, v8, v7
	v_fma_f32 v10, -v6, v9, v8
	v_fmac_f32_e32 v9, v10, v7
	v_fma_f32 v6, -v6, v9, v8
	v_div_fmas_f32 v6, v6, v7, v9
	v_div_fixup_f32 v1, v6, v1, 1.0
	v_div_scale_f32 v6, s[22:23], v0, v0, 1.0
	v_rcp_f32_e32 v7, v6
	s_nop 0
	v_fma_f32 v8, -v6, v7, 1.0
	v_fmac_f32_e32 v7, v8, v7
	v_div_scale_f32 v8, vcc, 1.0, v0, 1.0
	v_mul_f32_e32 v9, v8, v7
	v_fma_f32 v10, -v6, v9, v8
	v_fmac_f32_e32 v9, v10, v7
	v_fma_f32 v6, -v6, v9, v8
	v_div_fmas_f32 v6, v6, v7, v9
	v_div_fixup_f32 v0, v6, v0, 1.0
	v_div_scale_f32 v6, s[22:23], v3, v3, 1.0
	v_rcp_f32_e32 v7, v6
	s_nop 0
	v_fma_f32 v8, -v6, v7, 1.0
	v_fmac_f32_e32 v7, v8, v7
	v_div_scale_f32 v8, vcc, 1.0, v3, 1.0
	v_mul_f32_e32 v9, v8, v7
	v_fma_f32 v10, -v6, v9, v8
	v_fmac_f32_e32 v9, v10, v7
	v_fma_f32 v6, -v6, v9, v8
	v_div_fmas_f32 v6, v6, v7, v9
	v_div_fixup_f32 v3, v6, v3, 1.0
	v_div_scale_f32 v6, s[22:23], v2, v2, 1.0
	v_rcp_f32_e32 v7, v6
	s_nop 0
	v_fma_f32 v8, -v6, v7, 1.0
	v_fmac_f32_e32 v7, v8, v7
	v_div_scale_f32 v8, vcc, 1.0, v2, 1.0
	v_mul_f32_e32 v9, v8, v7
	v_fma_f32 v10, -v6, v9, v8
	v_fmac_f32_e32 v9, v10, v7
	v_fma_f32 v6, -v6, v9, v8
	v_div_fmas_f32 v6, v6, v7, v9
	v_div_fixup_f32 v2, v6, v2, 1.0
.LBB0_688:
	s_or_b64 exec, exec, s[4:5]
	v_cvt_pk_f16_f32 v2, v2, v3
	v_cvt_pk_f16_f32 v3, v0, v1
	v_mov_b32_e32 v0, v72
	v_mov_b32_e32 v1, v72
	v_mov_b32_e32 v232, v2
	v_mov_b32_e32 v233, v3
	v_pk_mul_f32 v[0:1], v[0:1], v[62:63]
	v_pk_mul_f32 v[2:3], v[72:73], v[60:61]
	s_and_saveexec_b64 s[4:5], s[20:21]
	s_cbranch_execz .LBB0_690
	v_mul_f32_e32 v0, 0xbfb8aa3b, v0
	v_mul_f32_e32 v1, 0xbfb8aa3b, v1
	v_exp_f32_e32 v0, v0
	v_exp_f32_e32 v1, v1
	v_mul_f32_e32 v2, 0xbfb8aa3b, v2
	v_mul_f32_e32 v3, 0xbfb8aa3b, v3
	v_exp_f32_e32 v2, v2
	v_pk_add_f32 v[0:1], v[0:1], 1.0 op_sel_hi:[1,0]
	v_exp_f32_e32 v3, v3
	v_div_scale_f32 v6, s[20:21], v1, v1, 1.0
	v_rcp_f32_e32 v7, v6
	v_pk_add_f32 v[2:3], v[2:3], 1.0 op_sel_hi:[1,0]
	v_fma_f32 v8, -v6, v7, 1.0
	v_fmac_f32_e32 v7, v8, v7
	v_div_scale_f32 v8, vcc, 1.0, v1, 1.0
	v_mul_f32_e32 v9, v8, v7
	v_fma_f32 v10, -v6, v9, v8
	v_fmac_f32_e32 v9, v10, v7
	v_fma_f32 v6, -v6, v9, v8
	v_div_fmas_f32 v6, v6, v7, v9
	v_div_fixup_f32 v1, v6, v1, 1.0
	v_div_scale_f32 v6, s[20:21], v0, v0, 1.0
	v_rcp_f32_e32 v7, v6
	s_nop 0
	v_fma_f32 v8, -v6, v7, 1.0
	v_fmac_f32_e32 v7, v8, v7
	v_div_scale_f32 v8, vcc, 1.0, v0, 1.0
	v_mul_f32_e32 v9, v8, v7
	v_fma_f32 v10, -v6, v9, v8
	v_fmac_f32_e32 v9, v10, v7
	v_fma_f32 v6, -v6, v9, v8
	v_div_fmas_f32 v6, v6, v7, v9
	v_div_fixup_f32 v0, v6, v0, 1.0
	v_div_scale_f32 v6, s[20:21], v3, v3, 1.0
	v_rcp_f32_e32 v7, v6
	s_nop 0
	v_fma_f32 v8, -v6, v7, 1.0
	v_fmac_f32_e32 v7, v8, v7
	v_div_scale_f32 v8, vcc, 1.0, v3, 1.0
	v_mul_f32_e32 v9, v8, v7
	v_fma_f32 v10, -v6, v9, v8
	v_fmac_f32_e32 v9, v10, v7
	v_fma_f32 v6, -v6, v9, v8
	v_div_fmas_f32 v6, v6, v7, v9
	v_div_fixup_f32 v3, v6, v3, 1.0
	v_div_scale_f32 v6, s[20:21], v2, v2, 1.0
	v_rcp_f32_e32 v7, v6
	s_nop 0
	v_fma_f32 v8, -v6, v7, 1.0
	v_fmac_f32_e32 v7, v8, v7
	v_div_scale_f32 v8, vcc, 1.0, v2, 1.0
	v_mul_f32_e32 v9, v8, v7
	v_fma_f32 v10, -v6, v9, v8
	v_fmac_f32_e32 v9, v10, v7
	v_fma_f32 v6, -v6, v9, v8
	v_div_fmas_f32 v6, v6, v7, v9
	v_div_fixup_f32 v2, v6, v2, 1.0
.LBB0_690:
	s_or_b64 exec, exec, s[4:5]
	v_cvt_pk_f16_f32 v2, v2, v3
	v_cvt_pk_f16_f32 v3, v0, v1
	s_mov_b64 s[4:5], 0
	v_mov_b32_e32 v234, v2
	v_mov_b32_e32 v235, v3
	v_and_b32_e32 v236, 16, v148
	v_lshrrev_b32_e32 v237, 1, v236
	v_add_u32_e32 v236, v236, v237
	v_mov_b32_e32 v237, 0
	v_lshl_add_u64 v[236:237], v[236:237], 0, v[4:5]
	v_permlane16_swap_b32_e32 v232, v234
	v_permlane16_swap_b32_e32 v233, v235
	global_store_dwordx4 v[236:237], v[232:235], off offset:64
